# no dry-run prefetch at all: only wait-placement fixes (hgaw hgcw hgci p0g), shared seam code and hand-written rotated seg5 epilogue; new GPU container
# speedup vs baseline: 1.0777x; 1.0074x over previous
; __global__ void __launch_bounds__(512, 2) mk_fwd(Args args) {
;     ...
;         for (int m4 = gw * 4; m4 < M_TOK; m4 += NGW * 4) {
;             f32x4 v[4][4]; float s2[4];
; #pragma unroll
;             for (int q = 0; q < 4; ++q) { const f32x4* xr = (const f32x4*)(x + (size_t)(m4 + q) * 1024) + lane;
; #pragma unroll
;                 for (int j = 0; j < 4; ++j) v[q][j] = xr[64 * j]; }
; #pragma unroll
;             for (int q = 0; q < 4; ++q) { s2[q] = 0.f;
; #pragma unroll
;                 for (int j = 0; j < 4; ++j) s2[q] += (v[q][j][0] * v[q][j][0] + v[q][j][1] * v[q][j][1]) + (v[q][j][2] * v[q][j][2] + v[q][j][3] * v[q][j][3]); }
; #pragma unroll
;             for (int o = 1; o < 64; o <<= 1) {
; #pragma unroll
;                 for (int q = 0; q < 4; ++q) s2[q] += __shfl_xor(s2[q], o); }
.LBB0_12:
	v_add_co_u32_e32 v20, vcc, 0x1000, v74
	global_load_dwordx4 v[4:7], v[74:75], off
	global_load_dwordx4 v[8:11], v[74:75], off offset:1024
	global_load_dwordx4 v[0:3], v[74:75], off offset:3072
	global_load_dwordx4 v[12:15], v[74:75], off offset:2048
	global_load_dwordx4 v[16:19], v[70:71], off
	v_addc_co_u32_e32 v21, vcc, 0, v75, vcc
	global_load_dwordx4 v[56:59], v[20:21], off
	global_load_dwordx4 v[60:63], v[20:21], off offset:1024
	global_load_dwordx4 v[52:55], v[20:21], off offset:3072
	global_load_dwordx4 v[64:67], v[20:21], off offset:2048
	v_add_co_u32_e32 v22, vcc, 0x2000, v74
	v_add_co_u32_e64 v76, s[4:5], s0, v72
	s_nop 0
	v_addc_co_u32_e32 v23, vcc, 0, v75, vcc
	global_load_dwordx4 v[48:51], v[22:23], off
	global_load_dwordx4 v[44:47], v[22:23], off offset:1024
	global_load_dwordx4 v[36:39], v[22:23], off offset:3072
	global_load_dwordx4 v[40:43], v[22:23], off offset:2048
	v_add_co_u32_e32 v78, vcc, 0x3000, v74
	v_addc_co_u32_e64 v77, s[4:5], 0, v73, s[4:5]
	s_nop 0
	v_addc_co_u32_e32 v79, vcc, 0, v75, vcc
	global_load_dwordx4 v[32:35], v[78:79], off
	global_load_dwordx4 v[28:31], v[78:79], off offset:1024
	global_load_dwordx4 v[24:27], v[78:79], off offset:2048
	global_load_dwordx4 v[20:23], v[78:79], off offset:3072
	v_add_u32_e32 v68, s10, v68
	v_cmp_lt_i32_e32 vcc, s11, v68
	s_or_b64 s[16:17], vcc, s[16:17]
	v_lshl_add_u64 v[74:75], v[74:75], 0, s[14:15]
	s_waitcnt vmcnt(16)
	v_pk_mul_f32 v[88:89], v[6:7], v[6:7]
	v_pk_mul_f32 v[90:91], v[4:5], v[4:5]
	s_waitcnt vmcnt(15)
	v_pk_mul_f32 v[100:101], v[10:11], v[10:11]
	v_pk_mul_f32 v[102:103], v[8:9], v[8:9]
	s_waitcnt vmcnt(14)
	v_mul_f32_e32 v99, v2, v2
	v_mul_f32_e32 v105, v3, v3
	s_waitcnt vmcnt(13)
	v_mul_f32_e32 v104, v13, v13
	v_mul_f32_e32 v106, v15, v15
	v_mul_f32_e32 v121, v0, v0
	v_mul_f32_e32 v124, v1, v1
	v_mov_b32_e32 v80, v4
	v_mov_b32_e32 v81, v6
	v_mov_b32_e32 v6, v5
	v_mov_b32_e32 v86, v0
	v_mov_b32_e32 v87, v2
	v_mov_b32_e32 v2, v1
	v_pk_mov_b32 v[0:1], v[90:91], v[88:89] op_sel:[1,0]
	v_mov_b32_e32 v91, v89
	v_pk_mov_b32 v[4:5], v[102:103], v[100:101] op_sel:[1,0]
	v_mov_b32_e32 v103, v101
	s_waitcnt vmcnt(12)
	v_mov_b32_e32 v78, v16
	v_mov_b32_e32 v79, v18
	v_mov_b32_e32 v18, v17
	v_mov_b32_e32 v82, v8
	v_mov_b32_e32 v83, v10
	v_mov_b32_e32 v10, v9
	v_pk_fma_f32 v[8:9], v[12:13], v[12:13], v[104:105] op_sel_hi:[1,1,0]
	v_pk_fma_f32 v[16:17], v[14:15], v[14:15], v[106:107] op_sel_hi:[1,1,0]
	v_pk_add_f32 v[0:1], v[0:1], v[90:91]
	v_pk_add_f32 v[4:5], v[4:5], v[102:103]
	v_mov_b32_e32 v84, v12
	v_mov_b32_e32 v85, v14
	v_mov_b32_e32 v14, v13
	v_mov_b32_e32 v9, v99
	v_mov_b32_e32 v17, v105
	s_waitcnt vmcnt(11)
	v_pk_mul_f32 v[12:13], v[58:59], v[58:59]
	v_pk_mul_f32 v[100:101], v[56:57], v[56:57]
	s_waitcnt vmcnt(10)
	v_pk_mul_f32 v[102:103], v[62:63], v[62:63]
	v_pk_mul_f32 v[104:105], v[60:61], v[60:61]
	s_waitcnt vmcnt(8)
	v_mul_f32_e32 v106, v65, v65
	v_pk_add_f32 v[110:111], v[0:1], v[0:1] op_sel:[0,1] op_sel_hi:[1,0]
	v_pk_add_f32 v[112:113], v[4:5], v[4:5] op_sel:[0,1] op_sel_hi:[1,0]
	v_mul_f32_e32 v99, v54, v54
	v_mul_f32_e32 v126, v52, v52
	v_mul_f32_e32 v127, v53, v53
	v_mov_b32_e32 v90, v52
	v_mov_b32_e32 v91, v54
	v_mov_b32_e32 v54, v53
	v_pk_add_f32 v[52:53], v[8:9], v[16:17]
	v_pk_mov_b32 v[16:17], v[100:101], v[12:13] op_sel:[1,0]
	v_mov_b32_e32 v101, v13
	v_pk_mov_b32 v[12:13], v[104:105], v[102:103] op_sel:[1,0]
	v_mov_b32_e32 v105, v103
	v_pk_fma_f32 v[102:103], v[64:65], v[64:65], v[106:107] op_sel_hi:[1,1,0]
	s_waitcnt vmcnt(7)
	v_pk_mul_f32 v[106:107], v[50:51], v[50:51]
	v_pk_mul_f32 v[114:115], v[48:49], v[48:49]
	s_waitcnt vmcnt(6)
	v_pk_mul_f32 v[116:117], v[46:47], v[46:47]
	v_pk_mul_f32 v[118:119], v[44:45], v[44:45]
	v_mov_b32_e32 v111, v121
	v_mov_b32_e32 v113, v124
	v_mul_f32_e32 v108, v67, v67
	v_mov_b32_e32 v122, v48
	v_mov_b32_e32 v123, v50
	v_mov_b32_e32 v50, v49
	v_pk_add_f32 v[48:49], v[16:17], v[100:101]
	v_pk_add_f32 v[100:101], v[12:13], v[104:105]
	v_pk_mov_b32 v[104:105], v[114:115], v[106:107] op_sel:[1,0]
	v_mov_b32_e32 v115, v107
	v_pk_mov_b32 v[106:107], v[118:119], v[116:117] op_sel:[1,0]
	v_mov_b32_e32 v119, v117
	v_pk_add_f32 v[110:111], v[110:111], v[112:113]
	v_mul_f32_e32 v125, v55, v55
	v_mov_b32_e32 v88, v56
	v_mov_b32_e32 v56, v60
	v_mov_b32_e32 v60, v64
	v_pk_fma_f32 v[108:109], v[66:67], v[66:67], v[108:109] op_sel_hi:[1,1,0]
	s_waitcnt vmcnt(4)
	v_mul_f32_e32 v64, v41, v41
	v_mul_f32_e32 v120, v43, v43
	v_pk_add_f32 v[104:105], v[104:105], v[114:115]
	v_pk_add_f32 v[106:107], v[106:107], v[118:119]
	v_pk_add_f32 v[48:49], v[48:49], v[48:49] op_sel:[0,1] op_sel_hi:[1,0]
	v_pk_add_f32 v[100:101], v[100:101], v[100:101] op_sel:[0,1] op_sel_hi:[1,0]
	v_pk_add_f32 v[52:53], v[110:111], v[52:53]
	v_mov_b32_e32 v89, v58
	v_mov_b32_e32 v58, v57
	v_mov_b32_e32 v57, v62
	v_mov_b32_e32 v62, v61
	v_mov_b32_e32 v61, v66
	v_mul_f32_e32 v128, v38, v38
	v_mul_f32_e32 v129, v39, v39
	v_mul_f32_e32 v130, v36, v36
	v_mul_f32_e32 v131, v37, v37
	v_mov_b32_e32 v66, v65
	v_mov_b32_e32 v4, v40
	v_mov_b32_e32 v103, v99
	v_mov_b32_e32 v109, v125
	v_pk_fma_f32 v[64:65], v[40:41], v[40:41], v[64:65] op_sel_hi:[1,1,0]
	v_pk_fma_f32 v[116:117], v[42:43], v[42:43], v[120:121] op_sel_hi:[1,1,0]
	v_mov_b32_e32 v49, v126
	v_mov_b32_e32 v101, v127
	v_pk_add_f32 v[104:105], v[104:105], v[104:105] op_sel:[0,1] op_sel_hi:[1,0]
	v_pk_add_f32 v[106:107], v[106:107], v[106:107] op_sel:[0,1] op_sel_hi:[1,0]
	v_add_f32_e32 v40, v52, v53
	v_mov_b32_e32 v5, v42
	v_pk_add_f32 v[102:103], v[102:103], v[108:109]
	v_mov_b32_e32 v65, v128
	v_mov_b32_e32 v117, v129
	v_pk_add_f32 v[48:49], v[48:49], v[100:101]
	v_mov_b32_e32 v105, v130
	v_mov_b32_e32 v107, v131
	ds_bpermute_b32 v42, v92, v40
	v_pk_add_f32 v[64:65], v[64:65], v[116:117]
	v_pk_add_f32 v[48:49], v[48:49], v[102:103]
	v_pk_add_f32 v[52:53], v[104:105], v[106:107]
	v_add_f32_e32 v48, v48, v49
	v_pk_add_f32 v[52:53], v[52:53], v[64:65]
	ds_bpermute_b32 v49, v92, v48
	v_add_f32_e32 v52, v52, v53
	ds_bpermute_b32 v53, v92, v52
	s_waitcnt lgkmcnt(2)
; __device__ __forceinline__ unsigned pk2(float lo, float hi) { return f2bf(lo) | (f2bf(hi) << 16); }
; __global__ void __launch_bounds__(512, 2) mk_fwd(Args args) {
;     ...
; #pragma unroll
;             for (int o = 1; o < 64; o <<= 1) {
; #pragma unroll
;                 for (int q = 0; q < 4; ++q) s2[q] += __shfl_xor(s2[q], o); }
; #pragma unroll
;             for (int q = 0; q < 4; ++q) {
;                 const float rstd = __builtin_amdgcn_rsqf(s2[q] * (1.f / 1024.f) + RMS_EPS);
;                 u32x2* o8 = (u32x2*)(Hn + (size_t)(m4 + q) * 1024) + lane;
; #pragma unroll
;                 for (int j = 0; j < 4; ++j) { const f32x4 gg = *((const f32x4*)norm_g + lane + 64 * j);
;                     o8[64 * j] = (u32x2){pk2(v[q][j][0] * rstd * gg[0], v[q][j][1] * rstd * gg[1]), pk2(v[q][j][2] * rstd * gg[2], v[q][j][3] * rstd * gg[3])}; }
;             }
	v_add_f32_e32 v40, v40, v42
	ds_bpermute_b32 v42, v93, v40
	s_waitcnt lgkmcnt(2)
	v_add_f32_e32 v48, v48, v49
	ds_bpermute_b32 v49, v93, v48
	s_waitcnt lgkmcnt(2)
	v_add_f32_e32 v52, v52, v53
	ds_bpermute_b32 v53, v93, v52
	s_waitcnt lgkmcnt(2)
	v_add_f32_e32 v40, v40, v42
	ds_bpermute_b32 v42, v94, v40
	s_waitcnt lgkmcnt(2)
	v_add_f32_e32 v48, v48, v49
	ds_bpermute_b32 v49, v94, v48
	s_waitcnt lgkmcnt(2)
	v_add_f32_e32 v52, v52, v53
	ds_bpermute_b32 v53, v94, v52
	s_waitcnt lgkmcnt(2)
	v_add_f32_e32 v40, v40, v42
	ds_bpermute_b32 v42, v95, v40
	s_waitcnt lgkmcnt(2)
	v_add_f32_e32 v48, v48, v49
	ds_bpermute_b32 v49, v95, v48
	s_waitcnt lgkmcnt(2)
	v_add_f32_e32 v52, v52, v53
	ds_bpermute_b32 v53, v95, v52
	s_waitcnt lgkmcnt(2)
	v_add_f32_e32 v40, v40, v42
	ds_bpermute_b32 v42, v96, v40
	s_waitcnt lgkmcnt(2)
	v_add_f32_e32 v48, v48, v49
	ds_bpermute_b32 v49, v96, v48
	s_waitcnt lgkmcnt(2)
	v_add_f32_e32 v52, v52, v53
	ds_bpermute_b32 v53, v96, v52
	s_waitcnt lgkmcnt(2)
	v_add_f32_e32 v40, v40, v42
	ds_bpermute_b32 v42, v97, v40
	s_waitcnt lgkmcnt(2)
	v_add_f32_e32 v48, v48, v49
	ds_bpermute_b32 v49, v97, v48
	s_waitcnt lgkmcnt(2)
	v_add_f32_e32 v52, v52, v53
	ds_bpermute_b32 v53, v97, v52
	s_waitcnt lgkmcnt(2)
	v_add_f32_e32 v40, v40, v42
	v_fmamk_f32 v40, v40, 0x3a800000, v69
	v_rsq_f32_e32 v42, v40
	s_waitcnt lgkmcnt(1)
	v_add_f32_e32 v40, v48, v49
	v_fmamk_f32 v40, v40, 0x3a800000, v69
	s_waitcnt lgkmcnt(0)
	v_add_f32_e32 v49, v52, v53
	v_rsq_f32_e32 v48, v40
	v_fmamk_f32 v40, v49, 0x3a800000, v69
	v_rsq_f32_e32 v40, v40
	v_pk_mul_f32 v[6:7], v[42:43], v[6:7] op_sel_hi:[0,1]
	v_pk_mul_f32 v[52:53], v[42:43], v[80:81] op_sel_hi:[0,1]
	v_pk_mul_f32 v[6:7], v[18:19], v[6:7]
	v_pk_mul_f32 v[18:19], v[78:79], v[52:53]
	v_pk_mul_f32 v[80:81], v[42:43], v[84:85] op_sel_hi:[0,1]
	v_and_b32_sdwa v49, v18, v98 dst_sel:DWORD dst_unused:UNUSED_PAD src0_sel:WORD_1 src1_sel:DWORD
	v_and_b32_sdwa v84, v7, v98 dst_sel:DWORD dst_unused:UNUSED_PAD src0_sel:WORD_1 src1_sel:DWORD
	v_and_b32_sdwa v85, v6, v98 dst_sel:DWORD dst_unused:UNUSED_PAD src0_sel:WORD_1 src1_sel:DWORD
	v_pk_mul_f32 v[10:11], v[42:43], v[10:11] op_sel_hi:[0,1]
	v_pk_mul_f32 v[14:15], v[42:43], v[14:15] op_sel_hi:[0,1]
	v_pk_mul_f32 v[64:65], v[42:43], v[82:83] op_sel_hi:[0,1]
	v_pk_mul_f32 v[2:3], v[42:43], v[2:3] op_sel_hi:[0,1]
	v_pk_mul_f32 v[82:83], v[42:43], v[86:87] op_sel_hi:[0,1]
	v_and_b32_sdwa v42, v19, v98 dst_sel:DWORD dst_unused:UNUSED_PAD src0_sel:WORD_1 src1_sel:DWORD
	v_pk_mul_f32 v[52:53], v[48:49], v[58:59] op_sel_hi:[0,1]
	v_pk_mul_f32 v[58:59], v[48:49], v[62:63] op_sel_hi:[0,1]
	v_pk_mul_f32 v[62:63], v[48:49], v[66:67] op_sel_hi:[0,1]
	v_pk_mul_f32 v[54:55], v[48:49], v[54:55] op_sel_hi:[0,1]
	v_pk_mul_f32 v[66:67], v[48:49], v[88:89] op_sel_hi:[0,1]
	v_pk_mul_f32 v[56:57], v[48:49], v[56:57] op_sel_hi:[0,1]
	v_pk_mul_f32 v[60:61], v[48:49], v[60:61] op_sel_hi:[0,1]
	v_pk_mul_f32 v[78:79], v[48:49], v[90:91] op_sel_hi:[0,1]
	v_add3_u32 v48, v18, v49, s1
	v_add3_u32 v49, v7, v84, s1
	v_add3_u32 v84, v6, v85, s1
	v_add3_u32 v42, v19, v42, s1
	v_pk_mul_f32 v[6:7], v[40:41], v[50:51] op_sel_hi:[0,1]
	v_and_b32_e32 v49, 0xffff0000, v49
	v_and_b32_e32 v50, 0xffff0000, v84
	v_or_b32_sdwa v49, v49, v42 dst_sel:DWORD dst_unused:UNUSED_PAD src0_sel:DWORD src1_sel:WORD_1
	v_or_b32_sdwa v48, v50, v48 dst_sel:DWORD dst_unused:UNUSED_PAD src0_sel:DWORD src1_sel:WORD_1
	global_store_dwordx2 v[72:73], v[48:49], off
	v_mov_b64_e32 v[48:49], v[228:229]
	v_pk_mul_f32 v[18:19], v[40:41], v[122:123] op_sel_hi:[0,1]
	v_mov_b32_e32 v8, v44
	v_mov_b32_e32 v9, v46
	v_mov_b32_e32 v46, v45
	v_mov_b32_e32 v0, v36
	v_mov_b32_e32 v1, v38
	v_mov_b32_e32 v38, v37
	s_waitcnt vmcnt(4)
	v_pk_mul_f32 v[44:45], v[34:35], v[34:35]
	v_pk_mul_f32 v[12:13], v[32:33], v[32:33]
	s_waitcnt vmcnt(3)
	v_pk_mul_f32 v[16:17], v[30:31], v[30:31]
	v_pk_mul_f32 v[36:37], v[28:29], v[28:29]
	s_waitcnt vmcnt(1)
	v_mul_f32_e32 v99, v20, v20
	v_pk_mul_f32 v[0:1], v[40:41], v[0:1] op_sel_hi:[0,1]
	v_mov_b64_e32 v[50:51], v[230:231]
	v_mov_b32_e32 v85, v50
	v_mov_b32_e32 v50, v49
	v_mov_b32_e32 v84, v48
	v_pk_mul_f32 v[10:11], v[50:51], v[10:11]
	v_pk_mul_f32 v[48:49], v[84:85], v[64:65]
	v_and_b32_sdwa v51, v11, v98 dst_sel:DWORD dst_unused:UNUSED_PAD src0_sel:WORD_1 src1_sel:DWORD
	v_and_b32_sdwa v64, v10, v98 dst_sel:DWORD dst_unused:UNUSED_PAD src0_sel:WORD_1 src1_sel:DWORD
	v_and_b32_sdwa v42, v49, v98 dst_sel:DWORD dst_unused:UNUSED_PAD src0_sel:WORD_1 src1_sel:DWORD
	v_and_b32_sdwa v50, v48, v98 dst_sel:DWORD dst_unused:UNUSED_PAD src0_sel:WORD_1 src1_sel:DWORD
	v_add3_u32 v11, v11, v51, s1
	v_add3_u32 v10, v10, v64, s1
	v_add3_u32 v48, v48, v50, s1
	v_add3_u32 v42, v49, v42, s1
	v_and_b32_e32 v11, 0xffff0000, v11
	v_and_b32_e32 v10, 0xffff0000, v10
	v_or_b32_sdwa v11, v11, v42 dst_sel:DWORD dst_unused:UNUSED_PAD src0_sel:DWORD src1_sel:WORD_1
	v_or_b32_sdwa v10, v10, v48 dst_sel:DWORD dst_unused:UNUSED_PAD src0_sel:DWORD src1_sel:WORD_1
	global_store_dwordx2 v[72:73], v[10:11], off offset:512
	v_mov_b64_e32 v[48:49], v[232:233]
	v_mov_b64_e32 v[50:51], v[234:235]
	v_mov_b32_e32 v11, v50
	v_mov_b32_e32 v50, v49
	v_mov_b32_e32 v10, v48
	v_pk_mul_f32 v[14:15], v[50:51], v[14:15]
	v_pk_mul_f32 v[10:11], v[10:11], v[80:81]
	v_and_b32_sdwa v49, v15, v98 dst_sel:DWORD dst_unused:UNUSED_PAD src0_sel:WORD_1 src1_sel:DWORD
	v_and_b32_sdwa v50, v14, v98 dst_sel:DWORD dst_unused:UNUSED_PAD src0_sel:WORD_1 src1_sel:DWORD
	v_and_b32_sdwa v42, v11, v98 dst_sel:DWORD dst_unused:UNUSED_PAD src0_sel:WORD_1 src1_sel:DWORD
	v_and_b32_sdwa v48, v10, v98 dst_sel:DWORD dst_unused:UNUSED_PAD src0_sel:WORD_1 src1_sel:DWORD
; __device__ __forceinline__ unsigned pk2(float lo, float hi) { return f2bf(lo) | (f2bf(hi) << 16); }
; __global__ void __launch_bounds__(512, 2) mk_fwd(Args args) {
;     ...
;             for (int q = 0; q < 4; ++q) {
;                 const float rstd = __builtin_amdgcn_rsqf(s2[q] * (1.f / 1024.f) + RMS_EPS);
;                 u32x2* o8 = (u32x2*)(Hn + (size_t)(m4 + q) * 1024) + lane;
; #pragma unroll
;                 for (int j = 0; j < 4; ++j) { const f32x4 gg = *((const f32x4*)norm_g + lane + 64 * j);
;                     o8[64 * j] = (u32x2){pk2(v[q][j][0] * rstd * gg[0], v[q][j][1] * rstd * gg[1]), pk2(v[q][j][2] * rstd * gg[2], v[q][j][3] * rstd * gg[3])}; }
;             }
	v_add3_u32 v15, v15, v49, s1
	v_add3_u32 v14, v14, v50, s1
	v_add3_u32 v10, v10, v48, s1
	v_add3_u32 v11, v11, v42, s1
	v_and_b32_e32 v15, 0xffff0000, v15
	v_and_b32_e32 v14, 0xffff0000, v14
	v_or_b32_sdwa v11, v15, v11 dst_sel:DWORD dst_unused:UNUSED_PAD src0_sel:DWORD src1_sel:WORD_1
	v_or_b32_sdwa v10, v14, v10 dst_sel:DWORD dst_unused:UNUSED_PAD src0_sel:DWORD src1_sel:WORD_1
	global_store_dwordx2 v[72:73], v[10:11], off offset:1024
	v_mov_b64_e32 v[48:49], v[236:237]
	v_mov_b64_e32 v[50:51], v[238:239]
	v_mov_b32_e32 v11, v50
	v_mov_b32_e32 v50, v49
	v_mov_b32_e32 v10, v48
	v_pk_mul_f32 v[2:3], v[50:51], v[2:3]
	v_pk_mul_f32 v[10:11], v[10:11], v[82:83]
	v_and_b32_sdwa v42, v3, v98 dst_sel:DWORD dst_unused:UNUSED_PAD src0_sel:WORD_1 src1_sel:DWORD
	v_and_b32_sdwa v48, v2, v98 dst_sel:DWORD dst_unused:UNUSED_PAD src0_sel:WORD_1 src1_sel:DWORD
	v_and_b32_sdwa v14, v11, v98 dst_sel:DWORD dst_unused:UNUSED_PAD src0_sel:WORD_1 src1_sel:DWORD
	v_and_b32_sdwa v15, v10, v98 dst_sel:DWORD dst_unused:UNUSED_PAD src0_sel:WORD_1 src1_sel:DWORD
	v_add3_u32 v3, v3, v42, s1
	v_add3_u32 v2, v2, v48, s1
	v_add3_u32 v10, v10, v15, s1
	v_add3_u32 v11, v11, v14, s1
	v_and_b32_e32 v3, 0xffff0000, v3
	v_and_b32_e32 v2, 0xffff0000, v2
	v_or_b32_sdwa v3, v3, v11 dst_sel:DWORD dst_unused:UNUSED_PAD src0_sel:DWORD src1_sel:WORD_1
	v_or_b32_sdwa v2, v2, v10 dst_sel:DWORD dst_unused:UNUSED_PAD src0_sel:DWORD src1_sel:WORD_1
	global_store_dwordx2 v[72:73], v[2:3], off offset:1536
	v_mov_b64_e32 v[48:49], v[224:225]
	v_mov_b64_e32 v[50:51], v[226:227]
	v_mov_b32_e32 v3, v50
	v_mov_b32_e32 v50, v49
	v_mov_b32_e32 v2, v48
	v_pk_mul_f32 v[10:11], v[50:51], v[52:53]
	v_pk_mul_f32 v[2:3], v[2:3], v[66:67]
	v_and_b32_sdwa v42, v11, v98 dst_sel:DWORD dst_unused:UNUSED_PAD src0_sel:WORD_1 src1_sel:DWORD
	v_and_b32_sdwa v48, v10, v98 dst_sel:DWORD dst_unused:UNUSED_PAD src0_sel:WORD_1 src1_sel:DWORD
	v_and_b32_sdwa v14, v3, v98 dst_sel:DWORD dst_unused:UNUSED_PAD src0_sel:WORD_1 src1_sel:DWORD
	v_and_b32_sdwa v15, v2, v98 dst_sel:DWORD dst_unused:UNUSED_PAD src0_sel:WORD_1 src1_sel:DWORD
	v_add3_u32 v11, v11, v42, s1
	v_add3_u32 v10, v10, v48, s1
	v_add3_u32 v2, v2, v15, s1
	v_add3_u32 v3, v3, v14, s1
	v_and_b32_e32 v11, 0xffff0000, v11
	v_and_b32_e32 v10, 0xffff0000, v10
	v_or_b32_sdwa v3, v11, v3 dst_sel:DWORD dst_unused:UNUSED_PAD src0_sel:DWORD src1_sel:WORD_1
	v_or_b32_sdwa v2, v10, v2 dst_sel:DWORD dst_unused:UNUSED_PAD src0_sel:DWORD src1_sel:WORD_1
	global_store_dwordx2 v[72:73], v[2:3], off offset:2048
	v_mov_b64_e32 v[48:49], v[228:229]
	v_mov_b64_e32 v[50:51], v[230:231]
	v_mov_b32_e32 v3, v50
	v_mov_b32_e32 v50, v49
	v_mov_b32_e32 v2, v48
	v_pk_mul_f32 v[10:11], v[50:51], v[58:59]
	v_pk_mul_f32 v[2:3], v[2:3], v[56:57]
	v_and_b32_sdwa v42, v11, v98 dst_sel:DWORD dst_unused:UNUSED_PAD src0_sel:WORD_1 src1_sel:DWORD
	v_and_b32_sdwa v48, v10, v98 dst_sel:DWORD dst_unused:UNUSED_PAD src0_sel:WORD_1 src1_sel:DWORD
	v_and_b32_sdwa v14, v3, v98 dst_sel:DWORD dst_unused:UNUSED_PAD src0_sel:WORD_1 src1_sel:DWORD
	v_and_b32_sdwa v15, v2, v98 dst_sel:DWORD dst_unused:UNUSED_PAD src0_sel:WORD_1 src1_sel:DWORD
	v_add3_u32 v11, v11, v42, s1
	v_add3_u32 v10, v10, v48, s1
	v_add3_u32 v2, v2, v15, s1
	v_add3_u32 v3, v3, v14, s1
	v_and_b32_e32 v11, 0xffff0000, v11
	v_and_b32_e32 v10, 0xffff0000, v10
	v_or_b32_sdwa v3, v11, v3 dst_sel:DWORD dst_unused:UNUSED_PAD src0_sel:DWORD src1_sel:WORD_1
	v_or_b32_sdwa v2, v10, v2 dst_sel:DWORD dst_unused:UNUSED_PAD src0_sel:DWORD src1_sel:WORD_1
	global_store_dwordx2 v[72:73], v[2:3], off offset:2560
	v_mov_b64_e32 v[48:49], v[232:233]
	v_mov_b64_e32 v[50:51], v[234:235]
	v_mov_b32_e32 v3, v50
	v_mov_b32_e32 v50, v49
	v_mov_b32_e32 v2, v48
	v_pk_mul_f32 v[10:11], v[50:51], v[62:63]
	v_pk_mul_f32 v[2:3], v[2:3], v[60:61]
	v_and_b32_sdwa v42, v11, v98 dst_sel:DWORD dst_unused:UNUSED_PAD src0_sel:WORD_1 src1_sel:DWORD
	v_and_b32_sdwa v48, v10, v98 dst_sel:DWORD dst_unused:UNUSED_PAD src0_sel:WORD_1 src1_sel:DWORD
	v_and_b32_sdwa v14, v3, v98 dst_sel:DWORD dst_unused:UNUSED_PAD src0_sel:WORD_1 src1_sel:DWORD
	v_and_b32_sdwa v15, v2, v98 dst_sel:DWORD dst_unused:UNUSED_PAD src0_sel:WORD_1 src1_sel:DWORD
	v_add3_u32 v11, v11, v42, s1
	v_add3_u32 v10, v10, v48, s1
	v_add3_u32 v2, v2, v15, s1
	v_add3_u32 v3, v3, v14, s1
	v_and_b32_e32 v11, 0xffff0000, v11
	v_and_b32_e32 v10, 0xffff0000, v10
	v_or_b32_sdwa v3, v11, v3 dst_sel:DWORD dst_unused:UNUSED_PAD src0_sel:DWORD src1_sel:WORD_1
	v_or_b32_sdwa v2, v10, v2 dst_sel:DWORD dst_unused:UNUSED_PAD src0_sel:DWORD src1_sel:WORD_1
	global_store_dwordx2 v[72:73], v[2:3], off offset:3072
	v_mov_b64_e32 v[48:49], v[236:237]
	v_mov_b64_e32 v[50:51], v[238:239]
	v_mov_b32_e32 v3, v50
	v_mov_b32_e32 v50, v49
	v_mov_b32_e32 v2, v48
	v_pk_mul_f32 v[10:11], v[50:51], v[54:55]
	v_pk_mul_f32 v[2:3], v[2:3], v[78:79]
	v_and_b32_sdwa v42, v11, v98 dst_sel:DWORD dst_unused:UNUSED_PAD src0_sel:WORD_1 src1_sel:DWORD
	v_and_b32_sdwa v48, v10, v98 dst_sel:DWORD dst_unused:UNUSED_PAD src0_sel:WORD_1 src1_sel:DWORD
	v_and_b32_sdwa v14, v3, v98 dst_sel:DWORD dst_unused:UNUSED_PAD src0_sel:WORD_1 src1_sel:DWORD
	v_and_b32_sdwa v15, v2, v98 dst_sel:DWORD dst_unused:UNUSED_PAD src0_sel:WORD_1 src1_sel:DWORD
	v_add3_u32 v11, v11, v42, s1
	v_add3_u32 v10, v10, v48, s1
	v_add3_u32 v2, v2, v15, s1
	v_add3_u32 v3, v3, v14, s1
	v_and_b32_e32 v11, 0xffff0000, v11
	v_and_b32_e32 v10, 0xffff0000, v10
	v_or_b32_sdwa v3, v11, v3 dst_sel:DWORD dst_unused:UNUSED_PAD src0_sel:DWORD src1_sel:WORD_1
	v_or_b32_sdwa v2, v10, v2 dst_sel:DWORD dst_unused:UNUSED_PAD src0_sel:DWORD src1_sel:WORD_1
	global_store_dwordx2 v[72:73], v[2:3], off offset:3584
; __device__ __forceinline__ unsigned pk2(float lo, float hi) { return f2bf(lo) | (f2bf(hi) << 16); }
; __global__ void __launch_bounds__(512, 2) mk_fwd(Args args) {
;     ...
;         for (int m4 = gw * 4; m4 < M_TOK; m4 += NGW * 4) {
;             f32x4 v[4][4]; float s2[4];
; #pragma unroll
;             for (int q = 0; q < 4; ++q) { const f32x4* xr = (const f32x4*)(x + (size_t)(m4 + q) * 1024) + lane;
; #pragma unroll
;                 for (int j = 0; j < 4; ++j) v[q][j] = xr[64 * j]; }
; #pragma unroll
;             for (int q = 0; q < 4; ++q) { s2[q] = 0.f;
; #pragma unroll
;                 for (int j = 0; j < 4; ++j) s2[q] += (v[q][j][0] * v[q][j][0] + v[q][j][1] * v[q][j][1]) + (v[q][j][2] * v[q][j][2] + v[q][j][3] * v[q][j][3]); }
; #pragma unroll
;             for (int o = 1; o < 64; o <<= 1) {
; #pragma unroll
;                 for (int q = 0; q < 4; ++q) s2[q] += __shfl_xor(s2[q], o); }
; #pragma unroll
;             for (int q = 0; q < 4; ++q) {
;                 const float rstd = __builtin_amdgcn_rsqf(s2[q] * (1.f / 1024.f) + RMS_EPS);
;                 u32x2* o8 = (u32x2*)(Hn + (size_t)(m4 + q) * 1024) + lane;
; #pragma unroll
;                 for (int j = 0; j < 4; ++j) { const f32x4 gg = *((const f32x4*)norm_g + lane + 64 * j);
;                     o8[64 * j] = (u32x2){pk2(v[q][j][0] * rstd * gg[0], v[q][j][1] * rstd * gg[1]), pk2(v[q][j][2] * rstd * gg[2], v[q][j][3] * rstd * gg[3])}; }
;             }
	v_mov_b64_e32 v[48:49], v[224:225]
	v_mov_b32_e32 v42, v41
	v_lshl_add_u64 v[72:73], v[72:73], 0, s[12:13]
	v_mov_b64_e32 v[50:51], v[226:227]
	v_mov_b32_e32 v3, v50
	v_mov_b32_e32 v50, v49
	v_mov_b32_e32 v2, v48
	v_pk_mul_f32 v[6:7], v[50:51], v[6:7]
	v_pk_mul_f32 v[2:3], v[2:3], v[18:19]
	v_and_b32_sdwa v14, v7, v98 dst_sel:DWORD dst_unused:UNUSED_PAD src0_sel:WORD_1 src1_sel:DWORD
	v_and_b32_sdwa v15, v6, v98 dst_sel:DWORD dst_unused:UNUSED_PAD src0_sel:WORD_1 src1_sel:DWORD
	v_and_b32_sdwa v10, v3, v98 dst_sel:DWORD dst_unused:UNUSED_PAD src0_sel:WORD_1 src1_sel:DWORD
	v_and_b32_sdwa v11, v2, v98 dst_sel:DWORD dst_unused:UNUSED_PAD src0_sel:WORD_1 src1_sel:DWORD
	v_add3_u32 v7, v7, v14, s1
	v_add3_u32 v6, v6, v15, s1
	v_add3_u32 v2, v2, v11, s1
	v_add3_u32 v3, v3, v10, s1
	v_and_b32_e32 v7, 0xffff0000, v7
	v_and_b32_e32 v6, 0xffff0000, v6
	v_or_b32_sdwa v3, v7, v3 dst_sel:DWORD dst_unused:UNUSED_PAD src0_sel:DWORD src1_sel:WORD_1
	v_or_b32_sdwa v2, v6, v2 dst_sel:DWORD dst_unused:UNUSED_PAD src0_sel:DWORD src1_sel:WORD_1
	global_store_dwordx2 v[76:77], v[2:3], off
	v_mov_b64_e32 v[48:49], v[228:229]
	v_pk_mul_f32 v[2:3], v[40:41], v[8:9] op_sel_hi:[0,1]
	v_pk_mul_f32 v[6:7], v[40:41], v[46:47] op_sel_hi:[0,1]
	v_mov_b32_e32 v18, v32
	v_mov_b32_e32 v19, v34
	v_mov_b32_e32 v34, v33
	v_pk_mov_b32 v[32:33], v[12:13], v[44:45] op_sel:[1,0]
	v_mov_b32_e32 v13, v45
	v_mul_f32_e32 v15, v21, v21
	v_mul_f32_e32 v14, v27, v27
	v_pk_add_f32 v[12:13], v[32:33], v[12:13]
	v_mul_f32_e32 v46, v22, v22
	v_mul_f32_e32 v47, v23, v23
	v_pk_add_f32 v[12:13], v[12:13], v[12:13] op_sel:[0,1] op_sel_hi:[1,0]
	v_mov_b64_e32 v[50:51], v[230:231]
	v_mov_b32_e32 v9, v50
	v_mov_b32_e32 v50, v49
	v_mov_b32_e32 v8, v48
	v_pk_mul_f32 v[6:7], v[50:51], v[6:7]
	v_pk_mul_f32 v[2:3], v[8:9], v[2:3]
	v_and_b32_sdwa v10, v7, v98 dst_sel:DWORD dst_unused:UNUSED_PAD src0_sel:WORD_1 src1_sel:DWORD
	v_and_b32_sdwa v11, v6, v98 dst_sel:DWORD dst_unused:UNUSED_PAD src0_sel:WORD_1 src1_sel:DWORD
	v_and_b32_sdwa v8, v3, v98 dst_sel:DWORD dst_unused:UNUSED_PAD src0_sel:WORD_1 src1_sel:DWORD
	v_and_b32_sdwa v9, v2, v98 dst_sel:DWORD dst_unused:UNUSED_PAD src0_sel:WORD_1 src1_sel:DWORD
	v_add3_u32 v7, v7, v10, s1
	v_add3_u32 v6, v6, v11, s1
	v_add3_u32 v2, v2, v9, s1
	v_add3_u32 v3, v3, v8, s1
	v_and_b32_e32 v7, 0xffff0000, v7
	v_and_b32_e32 v6, 0xffff0000, v6
	v_or_b32_sdwa v3, v7, v3 dst_sel:DWORD dst_unused:UNUSED_PAD src0_sel:DWORD src1_sel:WORD_1
	v_or_b32_sdwa v2, v6, v2 dst_sel:DWORD dst_unused:UNUSED_PAD src0_sel:DWORD src1_sel:WORD_1
	global_store_dwordx2 v[76:77], v[2:3], off offset:512
	v_mov_b64_e32 v[6:7], v[232:233]
	v_pk_mul_f32 v[2:3], v[40:41], v[4:5] op_sel_hi:[0,1]
	v_pk_mul_f32 v[4:5], v[40:41], v[42:43] op_sel_hi:[0,1]
	v_mul_f32_e32 v10, v25, v25
	v_mov_b32_e32 v13, v99
	v_mov_b64_e32 v[8:9], v[234:235]
	v_mov_b32_e32 v43, v8
	v_mov_b32_e32 v8, v7
	v_mov_b32_e32 v42, v6
	v_pk_mul_f32 v[4:5], v[8:9], v[4:5]
	v_pk_mul_f32 v[2:3], v[42:43], v[2:3]
	v_and_b32_sdwa v8, v5, v98 dst_sel:DWORD dst_unused:UNUSED_PAD src0_sel:WORD_1 src1_sel:DWORD
	v_and_b32_sdwa v9, v4, v98 dst_sel:DWORD dst_unused:UNUSED_PAD src0_sel:WORD_1 src1_sel:DWORD
	v_and_b32_sdwa v6, v3, v98 dst_sel:DWORD dst_unused:UNUSED_PAD src0_sel:WORD_1 src1_sel:DWORD
	v_and_b32_sdwa v7, v2, v98 dst_sel:DWORD dst_unused:UNUSED_PAD src0_sel:WORD_1 src1_sel:DWORD
	v_add3_u32 v5, v5, v8, s1
	v_add3_u32 v4, v4, v9, s1
	v_add3_u32 v2, v2, v7, s1
	v_add3_u32 v3, v3, v6, s1
	v_and_b32_e32 v5, 0xffff0000, v5
	v_and_b32_e32 v4, 0xffff0000, v4
	v_or_b32_sdwa v3, v5, v3 dst_sel:DWORD dst_unused:UNUSED_PAD src0_sel:DWORD src1_sel:WORD_1
	v_or_b32_sdwa v2, v4, v2 dst_sel:DWORD dst_unused:UNUSED_PAD src0_sel:DWORD src1_sel:WORD_1
	global_store_dwordx2 v[76:77], v[2:3], off offset:1024
	v_mov_b64_e32 v[2:3], v[236:237]
	v_pk_mov_b32 v[6:7], v[36:37], v[16:17] op_sel:[1,0]
	v_mov_b32_e32 v37, v17
	v_pk_add_f32 v[6:7], v[6:7], v[36:37]
	v_pk_fma_f32 v[8:9], v[24:25], v[24:25], v[10:11] op_sel_hi:[1,1,0]
	v_pk_fma_f32 v[10:11], v[26:27], v[26:27], v[14:15] op_sel_hi:[1,1,0]
	v_pk_add_f32 v[6:7], v[6:7], v[6:7] op_sel:[0,1] op_sel_hi:[1,0]
	v_mov_b32_e32 v9, v46
	v_mov_b32_e32 v11, v47
	v_mov_b32_e32 v7, v15
	v_pk_add_f32 v[8:9], v[8:9], v[10:11]
	v_pk_add_f32 v[6:7], v[12:13], v[6:7]
	s_nop 0
	v_pk_add_f32 v[6:7], v[6:7], v[8:9]
	v_mov_b64_e32 v[4:5], v[238:239]
	v_mov_b32_e32 v9, v4
	v_add_f32_e32 v6, v6, v7
	ds_bpermute_b32 v7, v92, v6
	v_mov_b32_e32 v4, v3
	v_mov_b32_e32 v8, v2
	v_pk_mul_f32 v[0:1], v[8:9], v[0:1]
	s_waitcnt lgkmcnt(0)
	v_add_f32_e32 v10, v6, v7
	v_pk_mul_f32 v[6:7], v[40:41], v[38:39] op_sel_hi:[0,1]
	v_pk_mul_f32 v[2:3], v[4:5], v[6:7]
	v_and_b32_sdwa v4, v1, v98 dst_sel:DWORD dst_unused:UNUSED_PAD src0_sel:WORD_1 src1_sel:DWORD
	v_and_b32_sdwa v6, v3, v98 dst_sel:DWORD dst_unused:UNUSED_PAD src0_sel:WORD_1 src1_sel:DWORD
	v_and_b32_sdwa v7, v2, v98 dst_sel:DWORD dst_unused:UNUSED_PAD src0_sel:WORD_1 src1_sel:DWORD
	v_and_b32_sdwa v5, v0, v98 dst_sel:DWORD dst_unused:UNUSED_PAD src0_sel:WORD_1 src1_sel:DWORD
	v_add3_u32 v3, v3, v6, s1
	v_add3_u32 v2, v2, v7, s1
	v_add3_u32 v0, v0, v5, s1
	v_add3_u32 v1, v1, v4, s1
	v_and_b32_e32 v3, 0xffff0000, v3
	v_and_b32_e32 v2, 0xffff0000, v2
	v_or_b32_sdwa v1, v3, v1 dst_sel:DWORD dst_unused:UNUSED_PAD src0_sel:DWORD src1_sel:WORD_1
	v_or_b32_sdwa v0, v2, v0 dst_sel:DWORD dst_unused:UNUSED_PAD src0_sel:DWORD src1_sel:WORD_1
	global_store_dwordx2 v[76:77], v[0:1], off offset:1536
	v_mov_b64_e32 v[0:1], v[224:225]
	ds_bpermute_b32 v4, v93, v10
	s_waitcnt lgkmcnt(0)
; __device__ __forceinline__ unsigned pk2(float lo, float hi) { return f2bf(lo) | (f2bf(hi) << 16); }
; __global__ void __launch_bounds__(512, 2) mk_fwd(Args args) {
;     ...
; #pragma unroll
;             for (int o = 1; o < 64; o <<= 1) {
; #pragma unroll
;                 for (int q = 0; q < 4; ++q) s2[q] += __shfl_xor(s2[q], o); }
; #pragma unroll
;             for (int q = 0; q < 4; ++q) {
;                 const float rstd = __builtin_amdgcn_rsqf(s2[q] * (1.f / 1024.f) + RMS_EPS);
;                 u32x2* o8 = (u32x2*)(Hn + (size_t)(m4 + q) * 1024) + lane;
; #pragma unroll
;                 for (int j = 0; j < 4; ++j) { const f32x4 gg = *((const f32x4*)norm_g + lane + 64 * j);
;                     o8[64 * j] = (u32x2){pk2(v[q][j][0] * rstd * gg[0], v[q][j][1] * rstd * gg[1]), pk2(v[q][j][2] * rstd * gg[2], v[q][j][3] * rstd * gg[3])}; }
;             }
	v_add_f32_e32 v4, v10, v4
	ds_bpermute_b32 v5, v94, v4
	s_waitcnt lgkmcnt(0)
	v_add_f32_e32 v4, v4, v5
	ds_bpermute_b32 v5, v95, v4
	s_waitcnt lgkmcnt(0)
	v_add_f32_e32 v4, v4, v5
	ds_bpermute_b32 v5, v96, v4
	s_waitcnt lgkmcnt(0)
	v_add_f32_e32 v4, v4, v5
	ds_bpermute_b32 v5, v97, v4
	s_waitcnt lgkmcnt(0)
	v_add_f32_e32 v4, v4, v5
	v_fmamk_f32 v4, v4, 0x3a800000, v69
	v_rsq_f32_e32 v4, v4
	v_mov_b64_e32 v[2:3], v[226:227]
	v_mov_b32_e32 v11, v2
	v_pk_mul_f32 v[8:9], v[4:5], v[34:35] op_sel_hi:[0,1]
	v_mov_b32_e32 v2, v1
	v_pk_mul_f32 v[6:7], v[4:5], v[18:19] op_sel_hi:[0,1]
	v_mov_b32_e32 v10, v0
	v_pk_mul_f32 v[2:3], v[2:3], v[8:9]
	v_pk_mul_f32 v[0:1], v[10:11], v[6:7]
	v_and_b32_sdwa v7, v3, v98 dst_sel:DWORD dst_unused:UNUSED_PAD src0_sel:WORD_1 src1_sel:DWORD
	v_and_b32_sdwa v8, v2, v98 dst_sel:DWORD dst_unused:UNUSED_PAD src0_sel:WORD_1 src1_sel:DWORD
	v_and_b32_sdwa v5, v1, v98 dst_sel:DWORD dst_unused:UNUSED_PAD src0_sel:WORD_1 src1_sel:DWORD
	v_and_b32_sdwa v6, v0, v98 dst_sel:DWORD dst_unused:UNUSED_PAD src0_sel:WORD_1 src1_sel:DWORD
	v_add3_u32 v3, v3, v7, s1
	v_add3_u32 v2, v2, v8, s1
	v_add3_u32 v0, v0, v6, s1
	v_add3_u32 v1, v1, v5, s1
	v_and_b32_e32 v3, 0xffff0000, v3
	v_and_b32_e32 v2, 0xffff0000, v2
	v_or_b32_sdwa v1, v3, v1 dst_sel:DWORD dst_unused:UNUSED_PAD src0_sel:DWORD src1_sel:WORD_1
	v_or_b32_sdwa v0, v2, v0 dst_sel:DWORD dst_unused:UNUSED_PAD src0_sel:DWORD src1_sel:WORD_1
	global_store_dwordx2 v[76:77], v[0:1], off offset:2048
	v_mov_b64_e32 v[0:1], v[228:229]
	v_mov_b32_e32 v7, v30
	v_mov_b32_e32 v30, v29
	v_mov_b32_e32 v6, v28
	v_pk_mul_f32 v[8:9], v[4:5], v[30:31] op_sel_hi:[0,1]
	v_pk_mul_f32 v[6:7], v[4:5], v[6:7] op_sel_hi:[0,1]
	v_mov_b64_e32 v[2:3], v[230:231]
	v_mov_b32_e32 v11, v2
	v_mov_b32_e32 v2, v1
	v_mov_b32_e32 v10, v0
	v_pk_mul_f32 v[2:3], v[2:3], v[8:9]
	v_pk_mul_f32 v[0:1], v[10:11], v[6:7]
	v_and_b32_sdwa v7, v3, v98 dst_sel:DWORD dst_unused:UNUSED_PAD src0_sel:WORD_1 src1_sel:DWORD
	v_and_b32_sdwa v8, v2, v98 dst_sel:DWORD dst_unused:UNUSED_PAD src0_sel:WORD_1 src1_sel:DWORD
	v_and_b32_sdwa v5, v1, v98 dst_sel:DWORD dst_unused:UNUSED_PAD src0_sel:WORD_1 src1_sel:DWORD
	v_and_b32_sdwa v6, v0, v98 dst_sel:DWORD dst_unused:UNUSED_PAD src0_sel:WORD_1 src1_sel:DWORD
	v_add3_u32 v3, v3, v7, s1
	v_add3_u32 v2, v2, v8, s1
	v_add3_u32 v0, v0, v6, s1
	v_add3_u32 v1, v1, v5, s1
	v_and_b32_e32 v3, 0xffff0000, v3
	v_and_b32_e32 v2, 0xffff0000, v2
	v_or_b32_sdwa v1, v3, v1 dst_sel:DWORD dst_unused:UNUSED_PAD src0_sel:DWORD src1_sel:WORD_1
	v_or_b32_sdwa v0, v2, v0 dst_sel:DWORD dst_unused:UNUSED_PAD src0_sel:DWORD src1_sel:WORD_1
	global_store_dwordx2 v[76:77], v[0:1], off offset:2560
	v_mov_b64_e32 v[0:1], v[232:233]
	v_mov_b32_e32 v7, v26
	v_mov_b32_e32 v26, v25
	v_mov_b32_e32 v6, v24
	v_pk_mul_f32 v[8:9], v[4:5], v[26:27] op_sel_hi:[0,1]
	v_pk_mul_f32 v[6:7], v[4:5], v[6:7] op_sel_hi:[0,1]
	v_mov_b64_e32 v[2:3], v[234:235]
	v_mov_b32_e32 v11, v2
	v_mov_b32_e32 v2, v1
	v_mov_b32_e32 v10, v0
	v_pk_mul_f32 v[2:3], v[2:3], v[8:9]
	v_pk_mul_f32 v[0:1], v[10:11], v[6:7]
	v_and_b32_sdwa v7, v3, v98 dst_sel:DWORD dst_unused:UNUSED_PAD src0_sel:WORD_1 src1_sel:DWORD
	v_and_b32_sdwa v8, v2, v98 dst_sel:DWORD dst_unused:UNUSED_PAD src0_sel:WORD_1 src1_sel:DWORD
	v_and_b32_sdwa v5, v1, v98 dst_sel:DWORD dst_unused:UNUSED_PAD src0_sel:WORD_1 src1_sel:DWORD
	v_and_b32_sdwa v6, v0, v98 dst_sel:DWORD dst_unused:UNUSED_PAD src0_sel:WORD_1 src1_sel:DWORD
	v_add3_u32 v3, v3, v7, s1
	v_add3_u32 v2, v2, v8, s1
	v_add3_u32 v0, v0, v6, s1
	v_add3_u32 v1, v1, v5, s1
	v_and_b32_e32 v3, 0xffff0000, v3
	v_and_b32_e32 v2, 0xffff0000, v2
	v_or_b32_sdwa v1, v3, v1 dst_sel:DWORD dst_unused:UNUSED_PAD src0_sel:DWORD src1_sel:WORD_1
	v_or_b32_sdwa v0, v2, v0 dst_sel:DWORD dst_unused:UNUSED_PAD src0_sel:DWORD src1_sel:WORD_1
	global_store_dwordx2 v[76:77], v[0:1], off offset:3072
	v_mov_b64_e32 v[0:1], v[236:237]
	v_mov_b32_e32 v6, v20
	v_mov_b32_e32 v7, v22
	v_mov_b32_e32 v22, v21
	v_pk_mul_f32 v[6:7], v[4:5], v[6:7] op_sel_hi:[0,1]
	v_pk_mul_f32 v[4:5], v[4:5], v[22:23] op_sel_hi:[0,1]
	v_mov_b64_e32 v[2:3], v[238:239]
	v_mov_b32_e32 v9, v2
	v_mov_b32_e32 v2, v1
	v_mov_b32_e32 v8, v0
	v_pk_mul_f32 v[2:3], v[2:3], v[4:5]
	v_pk_mul_f32 v[0:1], v[8:9], v[6:7]
	v_and_b32_sdwa v6, v3, v98 dst_sel:DWORD dst_unused:UNUSED_PAD src0_sel:WORD_1 src1_sel:DWORD
	v_and_b32_sdwa v7, v2, v98 dst_sel:DWORD dst_unused:UNUSED_PAD src0_sel:WORD_1 src1_sel:DWORD
	v_and_b32_sdwa v4, v1, v98 dst_sel:DWORD dst_unused:UNUSED_PAD src0_sel:WORD_1 src1_sel:DWORD
	v_and_b32_sdwa v5, v0, v98 dst_sel:DWORD dst_unused:UNUSED_PAD src0_sel:WORD_1 src1_sel:DWORD
	v_add3_u32 v3, v3, v6, s1
	v_add3_u32 v2, v2, v7, s1
	v_add3_u32 v0, v0, v5, s1
	v_add3_u32 v1, v1, v4, s1
	v_and_b32_e32 v3, 0xffff0000, v3
	v_and_b32_e32 v2, 0xffff0000, v2
	v_or_b32_sdwa v1, v3, v1 dst_sel:DWORD dst_unused:UNUSED_PAD src0_sel:DWORD src1_sel:WORD_1
	v_or_b32_sdwa v0, v2, v0 dst_sel:DWORD dst_unused:UNUSED_PAD src0_sel:DWORD src1_sel:WORD_1
	global_store_dwordx2 v[76:77], v[0:1], off offset:3584
	s_andn2_b64 exec, exec, s[16:17]
	s_cbranch_execnz .LBB0_12
